# v52: v50 + one static s_setprio 1 for waves 4-7 during P4 and P6 (reset at the following grid barriers)
# speedup vs baseline: 1.0015x; 1.0015x over previous
; #define LAS __attribute__((address_space(3)))
; template <bool FULL, bool PARTIAL  > ...
;     const int tid = threadIdx.x, lane = tid & 63, r = lane & 31, h = lane >> 5; const int w = __builtin_amdgcn_readfirstlane(tid >> 6);
;     const int kt = w & 3, tt = w >> 2, kk = 32 * kt + r;
;     const int nvalid = PARTIAL ? nvalid_ : 64;
;     LAS bf16_t* QS = (LAS bf16_t*)(lds + OFF_QS); LAS bf16_t* KS = (LAS bf16_t*)(lds + OFF_KS); LAS bf16_t* KdT = (LAS bf16_t*)(lds + OFF_KDT); LAS bf16_t* Ab = (LAS bf16_t*)(lds + OFF_A);
;     LAS bf16_t* VS = (LAS bf16_t*)(lds + OFF_VS); LAS float* GAs = (LAS float*)(lds + OFF_GA); LAS float* EB = (LAS float*)(lds + OFF_EB); LAS float* CS = (LAS float*)(lds + OFF_CS);
;     LAS float* PART = (LAS float*)(lds + OFF_PART);
;     float wal[8];
; #pragma unroll
;     for (int i = 0; i < 8; ++i) wal[i] = w_alpha[(2 * i + h) * 512 + hd * 128 + kk];
;     const float bal = b_alpha[hd * 128 + kk];
;     f32x16 Sacc[4];
;     float dsum = 0.f;
;     if (FULL && tid < 256) ((LAS float*)(lds + OFF_HN))[tid] = head_norm[tid];
;     f32x4 raw_ga; u32x4 raw_k[2], raw_q[2];
;     const int nv1 = nvalid - 1;
;     const u32x4 z4 = (u32x4){0u, 0u, 0u, 0u};
;     ...
;     GLA_FETCH_KG(0);
;     asm volatile("" :: "v"(raw_ga), "v"(raw_k[0]), "v"(raw_k[1]));
;     if (FULL) asm volatile("" :: "v"(raw_q[0]), "v"(raw_q[1]));
;     if (FULL && S0) {
;         const float* s0p = S0 + (size_t)(4 * h) * 256 + 32 * w + r;
; #pragma unroll
;         for (int kb = 0; kb < 4; ++kb)
; #pragma unroll
;             for (int i = 0; i < 16; ++i) Sacc[kb][i] = s0p[(32 * kb + (i & 3) + 8 * (i >> 2)) * 256];
;     } else {
; #pragma unroll
;         for (int kb = 0; kb < 4; ++kb)
; #pragma unroll
; __global__ void __launch_bounds__(NTHREADS, 2) fwd_kernel(Params P) {
;     ...
;     if (IN(4)) {
;     ...
;         for (int it = bx; it < 240; it += G) { const int bh = it / 15, sc = it % 15, b = bh >> 2, hd = bh & 3;
;             gla::span<false, false>(lds, b * SEQ + sc * 256, 4, 64, hd, QK, Vb, AB, GA, P.in[10], P.in[11], P.in[12], nullptr, DS + (size_t)it * 32768, DV + (size_t)it * 128); }
;     ...
;         for (int it = bx; it < 240; it += G) { const int bh = it / 15, sc = it % 15, b = bh >> 2, hd = bh & 3;
;             gla::span<false, false>(lds, b * SEQ + sc * 256, 4, 64, hd, QK, Vb, AB, GA, P.in[10], P.in[11], P.in[12], nullptr, DS + (size_t)it * 32768, DV + (size_t)it * 128); }
.Lxb3_end:
	s_barrier
	v_readfirstlane_b32 s100, v0
	s_lshr_b32 s100, s100, 8
	s_cmp_eq_u32 s100, 1
	s_cbranch_scc0 .Lprio_p4
	s_setprio 1
.Lprio_p4:
.LBB0_1038:
	v_readlane_b32 s4, v252, 28
	v_readlane_b32 s5, v252, 29
	s_cmp_lt_i32 s4, 5
	s_cselect_b64 s[4:5], -1, 0
	s_add_u32 s8, s68, 0x524000
	s_addc_u32 s9, s69, 0
	s_and_b64 s[20:21], s[4:5], s[0:1]
	s_andn2_b64 vcc, exec, s[20:21]
	s_cbranch_vccnz .LBB0_1195
	s_cmpk_gt_i32 s2, 0xef
	s_cbranch_scc1 .LBB0_1060
	s_waitcnt vmcnt(0)
	v_lshrrev_b32_e32 v5, 4, v0
	s_movk_i32 s3, 0x110
	v_lshlrev_b32_e32 v6, 4, v0
	v_mad_u32_u24 v5, v5, s3, 0
	v_and_b32_e32 v7, 0xf0, v6
	s_movk_i32 s4, 0x4400
	v_add3_u32 v125, v5, v7, s4
	v_lshlrev_b32_e32 v5, 2, v0
	v_lshrrev_b32_e32 v2, 5, v198
	v_and_b32_e32 v5, 12, v5
	v_and_b32_e32 v114, 31, v0
	s_add_i32 s0, 0, 0x1a700
	s_waitcnt lgkmcnt(0)
	v_lshlrev_b32_e32 v3, 4, v2
	v_mul_u32_u24_e32 v7, 0x110, v5
	s_add_i32 s4, 0, 0x18400
	v_and_b32_e32 v8, 0x1fc, v0
	v_add_u32_e32 v123, s0, v3
	s_add_i32 s0, 0, 0x19f00
	v_lshlrev_b32_e32 v4, 2, v114
	v_add3_u32 v126, s4, v7, v8
	v_mul_u32_u24_e32 v7, 0x110, v2
	v_add_u32_e32 v124, s0, v4
	v_add3_u32 v127, s4, v7, v4
	v_lshrrev_b32_e32 v4, 5, v0
	s_movk_i32 s6, 0x240
	v_mad_u32_u24 v4, v4, s6, 0
	v_and_b32_e32 v6, 0x1f0, v6
	s_mov_b32 s10, 0xf400
	v_add3_u32 v128, v4, v6, s10
	s_movk_i32 s10, 0x90
	v_mad_u32_u24 v4, v114, s10, 0
	s_mov_b32 s18, 0x8800
	v_add3_u32 v129, v4, v3, s18
	v_bfe_u32 v4, v0, 2, 2
	v_lshl_or_b32 v4, v2, 3, v4
	v_and_b32_e32 v6, 16, v0
	s_add_i32 s19, 0, 0x19500
	v_lshlrev_b32_e32 v115, 9, v2
	v_lshlrev_b32_e32 v122, 2, v2
	s_movk_i32 s0, 0x100
	v_mad_u32_u24 v4, v4, s6, 0
	v_lshlrev_b32_e32 v6, 1, v6
	v_lshlrev_b32_e32 v5, 1, v5
	s_cmp_lg_u64 s[50:51], 0
	v_mov_b32_e32 v117, 0
	v_lshlrev_b32_e32 v118, 12, v2
	v_mbcnt_lo_u32_b32 v2, -1, 0
	s_mov_b32 s7, 0
	v_cmp_gt_u32_e64 s[0:1], s0, v0
	v_cmp_gt_u32_e64 s[4:5], 32, v198
	v_add3_u32 v130, v4, v6, v5
	v_add_u32_e32 v131, s19, v3
	s_cselect_b64 s[10:11], -1, 0
	v_mov_b32_e32 v119, v117
	s_movk_i32 s33, 0x2000
	s_movk_i32 s38, 0x4000
	s_movk_i32 s39, 0x6000
	s_add_i32 s42, 0, 0x19700
	v_lshlrev_b32_e32 v132, 1, v122
	s_mov_b32 s43, 0xbfb8aa3b
	s_mov_b32 s44, 0x3d800000
	v_mbcnt_hi_u32_b32 v133, -1, v2
	s_mov_b32 s22, s2
	s_branch .LBB0_1042

; template <bool FULL, bool PARTIAL  > ...
;     const int tid = threadIdx.x, lane = tid & 63, r = lane & 31, h = lane >> 5; const int w = __builtin_amdgcn_readfirstlane(tid >> 6);
;     const int kt = w & 3, tt = w >> 2, kk = 32 * kt + r;
;     const int nvalid = PARTIAL ? nvalid_ : 64;
;     LAS bf16_t* QS = (LAS bf16_t*)(lds + OFF_QS); LAS bf16_t* KS = (LAS bf16_t*)(lds + OFF_KS); LAS bf16_t* KdT = (LAS bf16_t*)(lds + OFF_KDT); LAS bf16_t* Ab = (LAS bf16_t*)(lds + OFF_A);
;     LAS bf16_t* VS = (LAS bf16_t*)(lds + OFF_VS); LAS float* GAs = (LAS float*)(lds + OFF_GA); LAS float* EB = (LAS float*)(lds + OFF_EB); LAS float* CS = (LAS float*)(lds + OFF_CS);
;     LAS float* PART = (LAS float*)(lds + OFF_PART);
;     float wal[8];
; #pragma unroll
;     for (int i = 0; i < 8; ++i) wal[i] = w_alpha[(2 * i + h) * 512 + hd * 128 + kk];
;     const float bal = b_alpha[hd * 128 + kk];
;     f32x16 Sacc[4];
;     float dsum = 0.f;
;     if (FULL && tid < 256) ((LAS float*)(lds + OFF_HN))[tid] = head_norm[tid];
;     f32x4 raw_ga; u32x4 raw_k[2], raw_q[2];
;     const int nv1 = nvalid - 1;
;     const u32x4 z4 = (u32x4){0u, 0u, 0u, 0u};
;     ...
;     GLA_FETCH_KG(0);
;     asm volatile("" :: "v"(raw_ga), "v"(raw_k[0]), "v"(raw_k[1]));
;     if (FULL) asm volatile("" :: "v"(raw_q[0]), "v"(raw_q[1]));
;     if (FULL && S0) {
;         const float* s0p = S0 + (size_t)(4 * h) * 256 + 32 * w + r;
; #pragma unroll
;         for (int kb = 0; kb < 4; ++kb)
; #pragma unroll
;             for (int i = 0; i < 16; ++i) Sacc[kb][i] = s0p[(32 * kb + (i & 3) + 8 * (i >> 2)) * 256];
; __global__ void __launch_bounds__(NTHREADS, 2) fwd_kernel(Params P) {
;     ...
;     if (IN(6)) {
;     ...
;         for (int it = bx; it < 256; it += G) { const int bh = it >> 4, sc = it & 15, b = bh >> 2, hd = bh & 3;
;             gla::span<true, false>(lds, b * SEQ + sc * 256, 4, 64, hd, QK, Vb, AB, GA, P.in[10], P.in[11], P.in[12], sc ? DS + (size_t)(bh * 15 + sc - 1) * 32768 : nullptr, nullptr, nullptr, (bf16_t*)(outb + 53 * MiB)); }
;     ...
;         for (int it = bx; it < 256; it += G) { const int bh = it >> 4, sc = it & 15, b = bh >> 2, hd = bh & 3;
;             gla::span<true, false>(lds, b * SEQ + sc * 256, 4, 64, hd, QK, Vb, AB, GA, P.in[10], P.in[11], P.in[12], sc ? DS + (size_t)(bh * 15 + sc - 1) * 32768 : nullptr,
;                             sc == 15 ? out + OUT_GP + (size_t)bh * 32768 : nullptr, nullptr); }
.Lprio_p6:
.LBB0_1300:
	v_readlane_b32 s4, v252, 28
	v_readlane_b32 s5, v252, 29
	s_cmp_lt_i32 s4, 7
	s_cselect_b64 s[4:5], -1, 0
	s_and_b64 s[4:5], s[4:5], s[0:1]
	s_cmpk_lt_i32 s2, 0x100
	s_cselect_b64 s[76:77], -1, 0
	s_and_b64 s[0:1], s[4:5], s[76:77]
	s_andn2_b64 vcc, exec, s[0:1]
	s_movk_i32 s0, 0x100
	s_cbranch_vccnz .LBB0_1332
	v_writelane_b32 v252, s4, 36
	s_add_u32 s3, s50, 0x4200000
	s_waitcnt vmcnt(0)
	v_lshrrev_b32_e32 v5, 5, v198
	v_writelane_b32 v252, s5, 37
	s_addc_u32 s33, s51, 0
	v_and_b32_e32 v162, 31, v0
	v_lshlrev_b32_e32 v2, 2, v0
	s_waitcnt lgkmcnt(0)
	v_mov_b32_e32 v3, 0
	s_add_i32 s4, 0, 0x1a700
	v_lshlrev_b32_e32 v7, 4, v5
	v_lshrrev_b32_e32 v6, 4, v0
	s_movk_i32 s86, 0x110
	v_lshlrev_b32_e32 v9, 4, v0
	v_lshl_add_u64 v[164:165], s[60:61], 0, v[2:3]
	v_add_u32_e32 v216, s4, v2
	v_add_u32_e32 v218, s4, v7
	s_add_i32 s4, 0, 0x19f00
	v_lshlrev_b32_e32 v8, 2, v162
	v_mad_u32_u24 v6, v6, s86, 0
	v_and_b32_e32 v10, 0xf0, v9
	s_movk_i32 s87, 0x4400
	v_and_b32_e32 v2, 12, v2
	v_add_u32_e32 v219, s4, v8
	v_add3_u32 v220, v6, v10, s87
	v_mul_u32_u24_e32 v6, 0x110, v2
	s_add_i32 s4, 0, 0x18400
	v_and_b32_e32 v13, 0x1fc, v0
	v_add3_u32 v221, s4, v6, v13
	v_mul_u32_u24_e32 v13, 0x110, v5
	v_add3_u32 v222, s4, v13, v8
	v_lshrrev_b32_e32 v8, 5, v0
	s_movk_i32 s6, 0x240
	v_lshlrev_b32_e32 v10, 3, v5
	v_lshrrev_b32_e32 v12, 2, v0
	v_mad_u32_u24 v8, v8, s6, 0
	v_and_b32_e32 v9, 0x1f0, v9
	s_mov_b32 s7, 0xf400
	v_add3_u32 v223, v8, v9, s7
	v_and_or_b32 v8, v12, 3, v10
	v_and_b32_e32 v9, 16, v0
	v_mad_u32_u24 v8, v8, s6, 0
	v_lshlrev_b32_e32 v9, 1, v9
	v_lshlrev_b32_e32 v2, 1, v2
	v_add3_u32 v226, v8, v9, v2
	v_mul_u32_u24_e32 v2, 0x48, v162
	v_lshlrev_b32_e32 v217, 2, v5
	v_lshlrev_b32_e32 v2, 1, v2
	v_lshl_or_b32 v6, v162, 11, v217
	v_add3_u32 v2, 0, v2, v7
	v_add_u32_e32 v227, 0xd000, v2
	v_add_u32_e32 v228, 0x8800, v2
	v_lshlrev_b32_e32 v2, 1, v6
	v_lshlrev_b32_e32 v4, 10, v5
	v_add_u32_e32 v11, 0, v10
	s_add_i32 s88, 0, 0x19500
	v_lshl_add_u64 v[168:169], s[68:69], 0, v[2:3]
	v_mbcnt_lo_u32_b32 v2, -1, 0
	v_writelane_b32 v252, s76, 3
	v_lshlrev_b32_e32 v163, 9, v5
	v_cmp_gt_u32_e64 s[0:1], s0, v0
	s_mov_b32 s61, 0
	v_cmp_gt_u32_e64 s[4:5], 32, v198
	v_add_u32_e32 v224, v11, v10
	v_mad_u32_u24 v225, v162, s86, v11
	v_add_u32_e32 v229, s88, v7
	v_lshlrev_b32_e32 v166, 12, v5
	v_mov_b32_e32 v167, v3
	s_lshl_b32 s89, s2, 6
	s_lshl_b32 s42, s71, 6
	v_lshlrev_b32_e32 v170, 2, v4
	s_add_i32 s43, 0, 0x19700
	v_lshlrev_b32_e32 v172, 1, v6
	v_mov_b32_e32 v230, 0x358637bd
	s_mov_b32 s44, 0xbfb8aa3b
	s_mov_b32 s45, 0x3d800000
	v_lshlrev_b32_e32 v174, 2, v162
	v_mbcnt_hi_u32_b32 v231, -1, v2
	s_mov_b32 s78, s2
	s_mov_b32 s79, s2
	v_writelane_b32 v252, s77, 4
	s_branch .LBB0_1303
